# hybrid 3: XCD-wide re-alignment before every GEMM phase (P5, P7, P8, P1), row-block seams before the two norm_rows phases
# baseline (speedup 1.0000x reference)
; __device__ __forceinline__ void xcd_barrier(const XcdBarrier& b) {
;     asm volatile("s_waitcnt vmcnt(0)" ::: "memory");
;     __syncthreads();
;     if (threadIdx.x == 0) {
;         unsigned* bar = b.bar;
;         __builtin_amdgcn_s_waitcnt(0);
;         unsigned nloc = b.st[0], nx = b.st[1];
;         if (nloc == 0u) { xcd_barrier_complete(bar, b.x, nloc, nx); b.st[0] = nloc; b.st[1] = nx; }
.LBB0_503:
	v_readlane_b32 s20, v255, 24
	s_add_i32 s20, s20, 3
	s_cmp_lt_i32 s20, s59
	s_cselect_b64 s[26:27], -1, 0
	s_and_b64 s[4:5], s[4:5], s[26:27]
	s_andn2_b64 vcc, exec, s[4:5]
	s_cbranch_vccnz .LBB0_557
	s_waitcnt vmcnt(0)
	s_barrier
	s_and_saveexec_b64 s[4:5], s[74:75]
	s_cbranch_execz .LBB0_556
	s_cmp_lg_u32 s100, 0
	s_cbranch_scc1 .Lgs_known_15533
	v_readlane_b32 s22, v255, 6
	v_readlane_b32 s23, v255, 7
	s_nop 4
	global_load_dword v6, v1, s[22:23] offset:1024 sc1
	global_load_dword v7, v1, s[22:23] offset:1088 sc1
	global_load_dword v8, v1, s[22:23] offset:1152 sc1
	global_load_dword v9, v1, s[22:23] offset:1216 sc1
	global_load_dword v10, v1, s[22:23] offset:1280 sc1
	global_load_dword v11, v1, s[22:23] offset:1344 sc1
	global_load_dword v12, v1, s[22:23] offset:1408 sc1
	global_load_dword v13, v1, s[22:23] offset:1472 sc1
	s_waitcnt vmcnt(0)
	v_add_u32_e32 v14, -1, v6
	v_and_b32_e32 v14, v14, v6
	v_add_u32_e32 v15, -1, v7
	v_and_b32_e32 v15, v15, v7
	v_or_b32_e32 v14, v14, v15
	v_add_u32_e32 v15, -1, v8
	v_and_b32_e32 v15, v15, v8
	v_or_b32_e32 v14, v14, v15
	v_add_u32_e32 v15, -1, v9
	v_and_b32_e32 v15, v15, v9
	v_or_b32_e32 v14, v14, v15
	v_add_u32_e32 v15, -1, v10
	v_and_b32_e32 v15, v15, v10
	v_or_b32_e32 v14, v14, v15
	v_add_u32_e32 v15, -1, v11
	v_and_b32_e32 v15, v15, v11
	v_or_b32_e32 v14, v14, v15
	v_add_u32_e32 v15, -1, v12
	v_and_b32_e32 v15, v15, v12
	v_or_b32_e32 v14, v14, v15
	v_add_u32_e32 v15, -1, v13
	v_and_b32_e32 v15, v15, v13
	v_or_b32_e32 v14, v14, v15
	s_nop 0
	v_readfirstlane_b32 s22, v14
	s_cmp_eq_u32 s22, 0
	s_cselect_b32 s100, 1, 2
.Lgs_known_15533:
	v_readlane_b32 s22, v255, 27
	s_waitcnt vmcnt(0) expcnt(0) lgkmcnt(0)
	s_nop 0
	v_mov_b32_e32 v0, s22
	ds_read_b32 v3, v0
	v_readlane_b32 s22, v255, 28
	s_waitcnt lgkmcnt(0)
	v_cmp_ne_u32_e32 vcc, 0, v3
	v_mov_b32_e32 v0, s22
	ds_read_b32 v2, v0
	s_cbranch_vccnz .LBB0_520
	v_readlane_b32 s34, v254, 0
	v_readlane_b32 s35, v254, 1
	s_load_dwordx2 s[22:23], s[34:35], 0x4
	s_waitcnt lgkmcnt(0)
	s_mul_i32 s22, s22, s3
	s_mul_i32 s22, s22, s23
	s_mov_b32 s23, 1
	s_branch .LBB0_508

; __device__ __forceinline__ unsigned xb_ld(unsigned* p)              { return __hip_atomic_load(p, __ATOMIC_RELAXED, __HIP_MEMORY_SCOPE_AGENT); }
; __device__ __forceinline__ unsigned xb_add(unsigned* p, unsigned v) { return __hip_atomic_fetch_add(p, v, __ATOMIC_RELAXED, __HIP_MEMORY_SCOPE_AGENT); }
; #define XB_SPIN(cond, bar) do { unsigned _sp = 0; while (cond) { __builtin_amdgcn_s_sleep(1); \
;     if ((++_sp & 255u) == 0u) { if (xb_ld(&(bar)[XB_TMO])) break; if (_sp > XB_SPIN_CAP) { atomicAdd(&(bar)[XB_TMO], 1u); break; } } } } while (0)
; __device__ __forceinline__ void xcd_barrier(const XcdBarrier& b) {
;     ...
;         const unsigned old = xb_add(&bar[XB_XSUB(b.x)], 1u);
;         const unsigned gen = old / nloc;
;         if (old + 1u == (gen + 1u) * nloc) {
;             __builtin_amdgcn_fence(__ATOMIC_RELEASE, "agent");
;             asm volatile("s_waitcnt vmcnt(0)" ::: "memory");
;             const unsigned og = xb_add(&bar[XB_TOP], 1u);
;             const unsigned tg = og / nx;
;             if (og + 1u == (tg + 1u) * nx) xb_add(&bar[XB_TOPGEN], 1u);
;             else XB_SPIN(xb_ld(&bar[XB_TOPGEN]) == tg, bar);
;             __builtin_amdgcn_fence(__ATOMIC_ACQUIRE, "agent");
;             xb_add(&bar[XB_XGEN(b.x)], 1u);
;             asm volatile("s_waitcnt vmcnt(0)" ::: "memory");
;         } else {
;             XB_SPIN(xb_ld(&bar[XB_XGEN(b.x)]) == gen, bar);
;             __builtin_amdgcn_fence(__ATOMIC_ACQUIRE, "agent");
;             asm volatile("s_waitcnt vmcnt(0)" ::: "memory");
;         }
.LBB0_536:
	s_andn2_saveexec_b64 s[22:23], s[34:35]
	s_cbranch_execz .LBB0_556
	s_mov_b64 s[34:35], exec
	s_cmp_eq_u32 s100, 1
	s_cbranch_scc1 .LBB0_553
	buffer_wbl2 sc1
	s_waitcnt lgkmcnt(0)
	s_waitcnt vmcnt(0)
	v_mbcnt_lo_u32_b32 v0, s34, 0
	v_mbcnt_hi_u32_b32 v0, s35, v0
	v_cmp_eq_u32_e32 vcc, 0, v0
	s_and_saveexec_b64 s[36:37], vcc
	s_cbranch_execz .LBB0_539
	s_bcnt1_i32_b64 s22, s[34:35]
	v_mov_b32_e32 v3, s22
	v_readlane_b32 s22, v255, 6
	v_readlane_b32 s23, v255, 7
	s_nop 4
	global_atomic_add v3, v1, v3, s[22:23] sc0
.LBB0_539:
	s_or_b64 exec, exec, s[36:37]
	s_waitcnt vmcnt(0)
	v_readfirstlane_b32 s22, v3
	v_sub_u32_e32 v4, 0, v2
	s_mov_b64 s[36:37], -1
	v_add_u32_e32 v3, s22, v0
	v_cvt_f32_u32_e32 v0, v2
	v_readlane_b32 s22, v255, 8
	v_readlane_b32 s23, v255, 9
	v_rcp_iflag_f32_e32 v0, v0
	s_nop 0
	v_mul_f32_e32 v0, 0x4f7ffffe, v0
	v_cvt_u32_f32_e32 v0, v0
	v_mul_lo_u32 v4, v4, v0
	v_mul_hi_u32 v4, v0, v4
	v_add_u32_e32 v0, v0, v4
	v_mul_hi_u32 v0, v3, v0
	v_mul_lo_u32 v4, v0, v2
	v_sub_u32_e32 v4, v3, v4
	v_cmp_ge_u32_e32 vcc, v4, v2
	v_add_u32_e32 v5, 1, v0
	v_add_u32_e32 v3, 1, v3
	v_cndmask_b32_e32 v0, v0, v5, vcc
	v_sub_u32_e32 v5, v4, v2
	v_cndmask_b32_e32 v4, v4, v5, vcc
	v_cmp_ge_u32_e32 vcc, v4, v2
	v_add_u32_e32 v4, 1, v0
	s_nop 0
	v_cndmask_b32_e32 v0, v0, v4, vcc
	v_mul_lo_u32 v4, v2, v0
	v_add_u32_e32 v2, v4, v2
	v_cmp_ne_u32_e32 vcc, v3, v2
	v_mov_b64_e32 v[2:3], s[22:23]
	s_and_saveexec_b64 s[34:35], vcc
	s_cbranch_execz .LBB0_551
	v_readlane_b32 s22, v255, 8
	v_readlane_b32 s23, v255, 9
	s_mov_b64 s[38:39], 0
	s_nop 3
	global_load_dword v2, v1, s[22:23] sc1
	s_waitcnt vmcnt(0)
	v_cmp_eq_u32_e32 vcc, v2, v0
	s_and_saveexec_b64 s[36:37], vcc
	s_cbranch_execz .LBB0_550
	s_mov_b32 s22, 1
	s_branch .LBB0_543

; __device__ __forceinline__ void xcd_barrier(const XcdBarrier& b) {
;     asm volatile("s_waitcnt vmcnt(0)" ::: "memory");
;     __syncthreads();
;     if (threadIdx.x == 0) {
;         unsigned* bar = b.bar;
;         __builtin_amdgcn_s_waitcnt(0);
;         unsigned nloc = b.st[0], nx = b.st[1];
;         if (nloc == 0u) { xcd_barrier_complete(bar, b.x, nloc, nx); b.st[0] = nloc; b.st[1] = nx; }
.LBB0_711:
	v_readlane_b32 s20, v255, 24
	s_add_i32 s20, s20, 6
	s_waitcnt lgkmcnt(0)
	s_cmp_lt_i32 s20, s59
	s_cselect_b64 s[26:27], -1, 0
	s_and_b64 s[4:5], s[4:5], s[26:27]
	s_andn2_b64 vcc, exec, s[4:5]
	s_cbranch_vccnz .LBB0_765
	s_waitcnt vmcnt(0)
	s_waitcnt vmcnt(0)
	s_barrier
	s_and_saveexec_b64 s[4:5], s[74:75]
	s_cbranch_execz .LBB0_764
	s_cmp_lg_u32 s100, 0
	s_cbranch_scc1 .Lgs_known_20220
	v_readlane_b32 s22, v255, 6
	v_readlane_b32 s23, v255, 7
	s_nop 4
	global_load_dword v6, v1, s[22:23] offset:1024 sc1
	global_load_dword v7, v1, s[22:23] offset:1088 sc1
	global_load_dword v8, v1, s[22:23] offset:1152 sc1
	global_load_dword v9, v1, s[22:23] offset:1216 sc1
	global_load_dword v10, v1, s[22:23] offset:1280 sc1
	global_load_dword v11, v1, s[22:23] offset:1344 sc1
	global_load_dword v12, v1, s[22:23] offset:1408 sc1
	global_load_dword v13, v1, s[22:23] offset:1472 sc1
	s_waitcnt vmcnt(0)
	v_add_u32_e32 v14, -1, v6
	v_and_b32_e32 v14, v14, v6
	v_add_u32_e32 v15, -1, v7
	v_and_b32_e32 v15, v15, v7
	v_or_b32_e32 v14, v14, v15
	v_add_u32_e32 v15, -1, v8
	v_and_b32_e32 v15, v15, v8
	v_or_b32_e32 v14, v14, v15
	v_add_u32_e32 v15, -1, v9
	v_and_b32_e32 v15, v15, v9
	v_or_b32_e32 v14, v14, v15
	v_add_u32_e32 v15, -1, v10
	v_and_b32_e32 v15, v15, v10
	v_or_b32_e32 v14, v14, v15
	v_add_u32_e32 v15, -1, v11
	v_and_b32_e32 v15, v15, v11
	v_or_b32_e32 v14, v14, v15
	v_add_u32_e32 v15, -1, v12
	v_and_b32_e32 v15, v15, v12
	v_or_b32_e32 v14, v14, v15
	v_add_u32_e32 v15, -1, v13
	v_and_b32_e32 v15, v15, v13
	v_or_b32_e32 v14, v14, v15
	s_nop 0
	v_readfirstlane_b32 s22, v14
	s_cmp_eq_u32 s22, 0
	s_cselect_b32 s100, 1, 2
.Lgs_known_20220:
	v_readlane_b32 s22, v255, 27
	s_waitcnt vmcnt(0) expcnt(0) lgkmcnt(0)
	s_nop 0
	v_mov_b32_e32 v0, s22
	ds_read_b32 v3, v0
	v_readlane_b32 s22, v255, 28
	s_waitcnt lgkmcnt(0)
	v_cmp_ne_u32_e32 vcc, 0, v3
	v_mov_b32_e32 v0, s22
	ds_read_b32 v2, v0
	s_cbranch_vccnz .LBB0_728
	v_readlane_b32 s34, v254, 0
	v_readlane_b32 s35, v254, 1
	s_load_dwordx2 s[22:23], s[34:35], 0x4
	s_waitcnt lgkmcnt(0)
	s_mul_i32 s22, s22, s3
	s_mul_i32 s22, s22, s23
	s_mov_b32 s23, 1
	s_branch .LBB0_716
